# barrier census: the 16 per-XCD arrival counters loaded together (immediate offsets) instead of 16 serial load-wait pairs
# baseline (speedup 1.0000x reference)
.LBB0_557:
	v_readlane_b32 s14, v254, 6
	v_readlane_b32 s15, v254, 7
	s_mov_b64 s[16:17], -1
	s_waitcnt lgkmcnt(0)
	s_nop 3
	global_load_dword v0, v1, s[14:15] sc1
	global_load_dword v2, v1, s[14:15] offset:256 sc1
	global_load_dword v3, v1, s[14:15] offset:512 sc1
	global_load_dword v4, v1, s[14:15] offset:768 sc1
	global_load_dword v5, v1, s[14:15] offset:1024 sc1
	global_load_dword v6, v1, s[14:15] offset:1280 sc1
	global_load_dword v7, v1, s[14:15] offset:1536 sc1
	global_load_dword v8, v1, s[14:15] offset:1792 sc1
	global_load_dword v9, v1, s[14:15] offset:2048 sc1
	global_load_dword v10, v1, s[14:15] offset:2304 sc1
	global_load_dword v11, v1, s[14:15] offset:2560 sc1
	global_load_dword v12, v1, s[14:15] offset:2816 sc1
	global_load_dword v13, v1, s[14:15] offset:3072 sc1
	global_load_dword v14, v1, s[14:15] offset:3328 sc1
	global_load_dword v15, v1, s[14:15] offset:3584 sc1
	global_load_dword v16, v1, s[14:15] offset:3840 sc1
	s_mov_b64 s[14:15], -1
	s_waitcnt vmcnt(0)
	v_add_u32_e32 v17, v2, v0
	v_add_u32_e32 v17, v17, v3
	v_add_u32_e32 v17, v17, v4
	v_add_u32_e32 v17, v17, v5
	v_add_u32_e32 v17, v17, v6
	v_add_u32_e32 v17, v17, v7
	v_add_u32_e32 v17, v17, v8
	v_add_u32_e32 v17, v17, v9
	v_add_u32_e32 v17, v17, v10
	v_add_u32_e32 v17, v17, v11
	v_add_u32_e32 v17, v17, v12
	v_add_u32_e32 v17, v17, v13
	v_add_u32_e32 v17, v17, v14
	v_add_u32_e32 v17, v17, v15
	v_add_u32_e32 v17, v17, v16
	v_cmp_eq_u32_e32 vcc, s3, v17
	s_cbranch_vccnz .LBB0_556
	s_and_b32 s14, s10, 0xff
	s_cmp_eq_u32 s14, 0
	s_mov_b64 s[14:15], -1
	s_mov_b64 s[40:41], -1
	s_sleep 1
	s_cbranch_scc1 .LBB0_561
	s_and_b64 vcc, exec, s[40:41]
	s_cbranch_vccz .LBB0_556
